# t1 + nt (streaming) added to the sc1 in-proj epilogue stores
# speedup vs baseline: 1.0108x; 1.0024x over previous
; __device__ __forceinline__ unsigned cvt_pk_bf16(float lo, float hi) { f32x2_t v = {lo, hi}; bf16x2_t r = __builtin_convertvector(v, bf16x2_t); return __builtin_bit_cast(unsigned, r); }
; __device__ __forceinline__ float sigmoidf_(float v) { return __builtin_amdgcn_rcpf(1.0f + __builtin_amdgcn_exp2f(-1.4426950408889634f * v)); }
;     __device__ __forceinline__ void operator()(const f32x4 (&acc)[2][2][4][2], const Unit& u, int wr, int wc, int fr, int fq) const {
;     ...
; #pragma unroll
;         for (int ai = 0; ai < 2; ++ai)
; #pragma unroll
;             for (int m = 0; m < 4; ++m) { bf16_t* rowp = O + (size_t)(row0 + ai * HALF + m * 16) * NIN + col0;
; #pragma unroll
;                 for (int bj = 0; bj < 2; ++bj) { f32x4 v0 = acc[ai][bj][m][0], v1 = acc[ai][bj][m][1];
;                     if (mode != 0) {
; #pragma unroll
;                         for (int j = 0; j < 4; ++j) { v0[j] *= sigmoidf_(v0[j]); v1[j] *= sigmoidf_(v1[j]); }
;                     }
;                     u32x4 w; w.x = cvt_pk_bf16(v0[0], v0[1]); w.y = cvt_pk_bf16(v0[2], v0[3]); w.z = cvt_pk_bf16(v1[0], v1[1]); w.w = cvt_pk_bf16(v1[2], v1[3]);
;                     *(u32x4*)(rowp + bj * HALF) = w; } }
.LBB0_355:
	s_lshl_b32 s11, s44, 8
	s_add_i32 s11, s11, s54
	v_add_u32_e32 v141, s11, v154
	v_mov_b64_e32 v[138:139], s[4:5]
	v_ashrrev_i32_e32 v137, 31, v136
	v_mad_i64_i32 v[138:139], s[20:21], v141, s14, v[138:139]
	v_lshl_add_u64 v[138:139], v[136:137], 1, v[138:139]
	v_cvt_pk_bf16_f32 v128, v128, v129
	v_cvt_pk_bf16_f32 v129, v130, v131
	v_cvt_pk_bf16_f32 v130, v132, v133
	v_cvt_pk_bf16_f32 v131, v134, v135
	global_store_dwordx4 v[138:139], v[128:131], off sc1 nt
	v_mov_b64_e32 v[134:135], v[114:115]
	s_andn2_b64 vcc, exec, s[2:3]
	v_cndmask_b32_e64 v128, 0, 1, s[2:3]
	v_cmp_ne_u32_e64 s[38:39], 1, v128
	v_mov_b64_e32 v[130:131], v[118:119]
	v_mov_b64_e32 v[128:129], v[116:117]
	v_mov_b64_e32 v[132:133], v[112:113]
	s_cbranch_vccnz .LBB0_357
	v_mul_f32_e32 v129, 0xbfb8aa3b, v112
	v_mul_f32_e32 v130, 0xbfb8aa3b, v117
	v_exp_f32_e32 v129, v129
	v_exp_f32_e32 v130, v130
	v_mul_f32_e32 v131, 0xbfb8aa3b, v118
	v_mul_f32_e32 v133, 0xbfb8aa3b, v114
	v_add_f32_e32 v129, 1.0, v129
	v_rcp_f32_e32 v132, v129
	v_add_f32_e32 v129, 1.0, v130
	v_mul_f32_e32 v130, 0xbfb8aa3b, v113
	v_exp_f32_e32 v130, v130
	v_exp_f32_e32 v131, v131
	v_exp_f32_e32 v133, v133
	v_mul_f32_e32 v128, 0xbfb8aa3b, v116
	v_add_f32_e32 v142, 1.0, v130
	v_add_f32_e32 v130, 1.0, v131
	v_add_f32_e32 v131, 1.0, v133
	v_mul_f32_e32 v133, 0xbfb8aa3b, v119
	v_mul_f32_e32 v134, 0xbfb8aa3b, v115
	v_exp_f32_e32 v128, v128
	v_exp_f32_e32 v133, v133
	v_exp_f32_e32 v135, v134
	v_rcp_f32_e32 v134, v131
	v_add_f32_e32 v128, 1.0, v128
	v_add_f32_e32 v131, 1.0, v133
	v_add_f32_e32 v133, 1.0, v135
	v_rcp_f32_e32 v128, v128
	v_rcp_f32_e32 v129, v129
	v_rcp_f32_e32 v130, v130
	v_rcp_f32_e32 v131, v131
	v_rcp_f32_e32 v135, v133
	v_rcp_f32_e32 v133, v142
	v_pk_mul_f32 v[128:129], v[116:117], v[128:129]
	v_pk_mul_f32 v[130:131], v[118:119], v[130:131]
	v_pk_mul_f32 v[134:135], v[114:115], v[134:135]
	v_pk_mul_f32 v[132:133], v[112:113], v[132:133]
.LBB0_357:
	v_cvt_pk_bf16_f32 v128, v128, v129
	v_cvt_pk_bf16_f32 v129, v130, v131
	v_cvt_pk_bf16_f32 v130, v132, v133
	v_cvt_pk_bf16_f32 v131, v134, v135
	global_store_dwordx4 v[138:139], v[128:131], off offset:256 sc1 nt
	v_mov_b64_e32 v[134:135], v[106:107]
	s_and_b64 vcc, exec, s[38:39]
	v_mov_b64_e32 v[130:131], v[110:111]
	v_mov_b64_e32 v[128:129], v[108:109]
	v_mov_b64_e32 v[132:133], v[104:105]
	s_cbranch_vccnz .LBB0_359
	v_mul_f32_e32 v129, 0xbfb8aa3b, v104
	v_mul_f32_e32 v130, 0xbfb8aa3b, v109
	v_exp_f32_e32 v129, v129
	v_exp_f32_e32 v130, v130
	v_mul_f32_e32 v131, 0xbfb8aa3b, v110
	v_mul_f32_e32 v133, 0xbfb8aa3b, v106
	v_add_f32_e32 v129, 1.0, v129
	v_rcp_f32_e32 v132, v129
	v_add_f32_e32 v129, 1.0, v130
	v_mul_f32_e32 v130, 0xbfb8aa3b, v105
	v_exp_f32_e32 v130, v130
	v_exp_f32_e32 v131, v131
	v_exp_f32_e32 v133, v133
	v_mul_f32_e32 v128, 0xbfb8aa3b, v108
	v_add_f32_e32 v138, 1.0, v130
	v_add_f32_e32 v130, 1.0, v131
	v_add_f32_e32 v131, 1.0, v133
	v_mul_f32_e32 v133, 0xbfb8aa3b, v111
	v_mul_f32_e32 v134, 0xbfb8aa3b, v107
	v_exp_f32_e32 v128, v128
	v_exp_f32_e32 v133, v133
	v_exp_f32_e32 v135, v134
	v_rcp_f32_e32 v134, v131
	v_add_f32_e32 v128, 1.0, v128
	v_add_f32_e32 v131, 1.0, v133
	v_add_f32_e32 v133, 1.0, v135
	v_rcp_f32_e32 v128, v128
	v_rcp_f32_e32 v129, v129
	v_rcp_f32_e32 v130, v130
	v_rcp_f32_e32 v131, v131
	v_rcp_f32_e32 v135, v133
	v_rcp_f32_e32 v133, v138
	v_pk_mul_f32 v[128:129], v[108:109], v[128:129]
	v_pk_mul_f32 v[130:131], v[110:111], v[130:131]
	v_pk_mul_f32 v[134:135], v[106:107], v[134:135]
	v_pk_mul_f32 v[132:133], v[104:105], v[132:133]
.LBB0_359:
	v_add_u32_e32 v142, 16, v141
	v_mov_b64_e32 v[138:139], s[4:5]
	v_mad_i64_i32 v[138:139], s[2:3], v142, s14, v[138:139]
	v_lshl_add_u64 v[138:139], v[136:137], 1, v[138:139]
	v_cvt_pk_bf16_f32 v128, v128, v129
	v_cvt_pk_bf16_f32 v129, v130, v131
	v_cvt_pk_bf16_f32 v130, v132, v133
	v_cvt_pk_bf16_f32 v131, v134, v135
	global_store_dwordx4 v[138:139], v[128:131], off sc1 nt
	v_mov_b64_e32 v[134:135], v[98:99]
	s_and_b64 vcc, exec, s[38:39]
	v_mov_b64_e32 v[130:131], v[102:103]
	v_mov_b64_e32 v[128:129], v[100:101]
	v_mov_b64_e32 v[132:133], v[96:97]
	s_cbranch_vccnz .LBB0_361
	v_mul_f32_e32 v129, 0xbfb8aa3b, v96
	v_mul_f32_e32 v130, 0xbfb8aa3b, v101
	v_exp_f32_e32 v129, v129
	v_exp_f32_e32 v130, v130
	v_mul_f32_e32 v131, 0xbfb8aa3b, v102
	v_mul_f32_e32 v133, 0xbfb8aa3b, v98
	v_add_f32_e32 v129, 1.0, v129
	v_rcp_f32_e32 v132, v129
	v_add_f32_e32 v129, 1.0, v130
	v_mul_f32_e32 v130, 0xbfb8aa3b, v97
	v_exp_f32_e32 v130, v130
	v_exp_f32_e32 v131, v131
	v_exp_f32_e32 v133, v133
	v_mul_f32_e32 v128, 0xbfb8aa3b, v100
	v_add_f32_e32 v142, 1.0, v130
	v_add_f32_e32 v130, 1.0, v131
	v_add_f32_e32 v131, 1.0, v133
	v_mul_f32_e32 v133, 0xbfb8aa3b, v103
	v_mul_f32_e32 v134, 0xbfb8aa3b, v99
	v_exp_f32_e32 v128, v128
	v_exp_f32_e32 v133, v133
	v_exp_f32_e32 v135, v134
	v_rcp_f32_e32 v134, v131
	v_add_f32_e32 v128, 1.0, v128
	v_add_f32_e32 v131, 1.0, v133
	v_add_f32_e32 v133, 1.0, v135
	v_rcp_f32_e32 v128, v128
	v_rcp_f32_e32 v129, v129
	v_rcp_f32_e32 v130, v130
	v_rcp_f32_e32 v131, v131
	v_rcp_f32_e32 v135, v133
	v_rcp_f32_e32 v133, v142
	v_pk_mul_f32 v[128:129], v[100:101], v[128:129]
	v_pk_mul_f32 v[130:131], v[102:103], v[130:131]
	v_pk_mul_f32 v[134:135], v[98:99], v[134:135]
	v_pk_mul_f32 v[132:133], v[96:97], v[132:133]
; __device__ __forceinline__ unsigned cvt_pk_bf16(float lo, float hi) { f32x2_t v = {lo, hi}; bf16x2_t r = __builtin_convertvector(v, bf16x2_t); return __builtin_bit_cast(unsigned, r); }
; __device__ __forceinline__ float sigmoidf_(float v) { return __builtin_amdgcn_rcpf(1.0f + __builtin_amdgcn_exp2f(-1.4426950408889634f * v)); }
;     __device__ __forceinline__ void operator()(const f32x4 (&acc)[2][2][4][2], const Unit& u, int wr, int wc, int fr, int fq) const {
;     ...
; #pragma unroll
;         for (int ai = 0; ai < 2; ++ai)
; #pragma unroll
;             for (int m = 0; m < 4; ++m) { bf16_t* rowp = O + (size_t)(row0 + ai * HALF + m * 16) * NIN + col0;
; #pragma unroll
;                 for (int bj = 0; bj < 2; ++bj) { f32x4 v0 = acc[ai][bj][m][0], v1 = acc[ai][bj][m][1];
;                     if (mode != 0) {
; #pragma unroll
;                         for (int j = 0; j < 4; ++j) { v0[j] *= sigmoidf_(v0[j]); v1[j] *= sigmoidf_(v1[j]); }
;                     }
;                     u32x4 w; w.x = cvt_pk_bf16(v0[0], v0[1]); w.y = cvt_pk_bf16(v0[2], v0[3]); w.z = cvt_pk_bf16(v1[0], v1[1]); w.w = cvt_pk_bf16(v1[2], v1[3]);
;                     *(u32x4*)(rowp + bj * HALF) = w; } }
.LBB0_361:
	v_cvt_pk_bf16_f32 v128, v128, v129
	v_cvt_pk_bf16_f32 v129, v130, v131
	v_cvt_pk_bf16_f32 v130, v132, v133
	v_cvt_pk_bf16_f32 v131, v134, v135
	global_store_dwordx4 v[138:139], v[128:131], off offset:256 sc1 nt
	v_mov_b64_e32 v[134:135], v[90:91]
	s_and_b64 vcc, exec, s[38:39]
	v_mov_b64_e32 v[130:131], v[94:95]
	v_mov_b64_e32 v[128:129], v[92:93]
	v_mov_b64_e32 v[132:133], v[88:89]
	s_cbranch_vccnz .LBB0_363
	v_mul_f32_e32 v129, 0xbfb8aa3b, v88
	v_mul_f32_e32 v130, 0xbfb8aa3b, v93
	v_exp_f32_e32 v129, v129
	v_exp_f32_e32 v130, v130
	v_mul_f32_e32 v131, 0xbfb8aa3b, v94
	v_mul_f32_e32 v133, 0xbfb8aa3b, v90
	v_add_f32_e32 v129, 1.0, v129
	v_rcp_f32_e32 v132, v129
	v_add_f32_e32 v129, 1.0, v130
	v_mul_f32_e32 v130, 0xbfb8aa3b, v89
	v_exp_f32_e32 v130, v130
	v_exp_f32_e32 v131, v131
	v_exp_f32_e32 v133, v133
	v_mul_f32_e32 v128, 0xbfb8aa3b, v92
	v_add_f32_e32 v138, 1.0, v130
	v_add_f32_e32 v130, 1.0, v131
	v_add_f32_e32 v131, 1.0, v133
	v_mul_f32_e32 v133, 0xbfb8aa3b, v95
	v_mul_f32_e32 v134, 0xbfb8aa3b, v91
	v_exp_f32_e32 v128, v128
	v_exp_f32_e32 v133, v133
	v_exp_f32_e32 v135, v134
	v_rcp_f32_e32 v134, v131
	v_add_f32_e32 v128, 1.0, v128
	v_add_f32_e32 v131, 1.0, v133
	v_add_f32_e32 v133, 1.0, v135
	v_rcp_f32_e32 v128, v128
	v_rcp_f32_e32 v129, v129
	v_rcp_f32_e32 v130, v130
	v_rcp_f32_e32 v131, v131
	v_rcp_f32_e32 v135, v133
	v_rcp_f32_e32 v133, v138
	v_pk_mul_f32 v[128:129], v[92:93], v[128:129]
	v_pk_mul_f32 v[130:131], v[94:95], v[130:131]
	v_pk_mul_f32 v[134:135], v[90:91], v[134:135]
	v_pk_mul_f32 v[132:133], v[88:89], v[132:133]
.LBB0_363:
	v_add_u32_e32 v142, 32, v141
	v_mov_b64_e32 v[138:139], s[4:5]
	v_mad_i64_i32 v[138:139], s[2:3], v142, s14, v[138:139]
	v_lshl_add_u64 v[138:139], v[136:137], 1, v[138:139]
	v_cvt_pk_bf16_f32 v128, v128, v129
	v_cvt_pk_bf16_f32 v129, v130, v131
	v_cvt_pk_bf16_f32 v130, v132, v133
	v_cvt_pk_bf16_f32 v131, v134, v135
	global_store_dwordx4 v[138:139], v[128:131], off sc1 nt
	v_mov_b64_e32 v[134:135], v[82:83]
	s_and_b64 vcc, exec, s[38:39]
	v_mov_b64_e32 v[130:131], v[86:87]
	v_mov_b64_e32 v[128:129], v[84:85]
	v_mov_b64_e32 v[132:133], v[80:81]
	s_cbranch_vccnz .LBB0_365
	v_mul_f32_e32 v129, 0xbfb8aa3b, v80
	v_mul_f32_e32 v130, 0xbfb8aa3b, v85
	v_exp_f32_e32 v129, v129
	v_exp_f32_e32 v130, v130
	v_mul_f32_e32 v131, 0xbfb8aa3b, v86
	v_mul_f32_e32 v133, 0xbfb8aa3b, v82
	v_add_f32_e32 v129, 1.0, v129
	v_rcp_f32_e32 v132, v129
	v_add_f32_e32 v129, 1.0, v130
	v_mul_f32_e32 v130, 0xbfb8aa3b, v81
	v_exp_f32_e32 v130, v130
	v_exp_f32_e32 v131, v131
	v_exp_f32_e32 v133, v133
	v_mul_f32_e32 v128, 0xbfb8aa3b, v84
	v_add_f32_e32 v142, 1.0, v130
	v_add_f32_e32 v130, 1.0, v131
	v_add_f32_e32 v131, 1.0, v133
	v_mul_f32_e32 v133, 0xbfb8aa3b, v87
	v_mul_f32_e32 v134, 0xbfb8aa3b, v83
	v_exp_f32_e32 v128, v128
	v_exp_f32_e32 v133, v133
	v_exp_f32_e32 v135, v134
	v_rcp_f32_e32 v134, v131
	v_add_f32_e32 v128, 1.0, v128
	v_add_f32_e32 v131, 1.0, v133
	v_add_f32_e32 v133, 1.0, v135
	v_rcp_f32_e32 v128, v128
	v_rcp_f32_e32 v129, v129
	v_rcp_f32_e32 v130, v130
	v_rcp_f32_e32 v131, v131
	v_rcp_f32_e32 v135, v133
	v_rcp_f32_e32 v133, v142
	v_pk_mul_f32 v[128:129], v[84:85], v[128:129]
	v_pk_mul_f32 v[130:131], v[86:87], v[130:131]
	v_pk_mul_f32 v[134:135], v[82:83], v[134:135]
	v_pk_mul_f32 v[132:133], v[80:81], v[132:133]
.LBB0_365:
	v_cvt_pk_bf16_f32 v128, v128, v129
	v_cvt_pk_bf16_f32 v129, v130, v131
	v_cvt_pk_bf16_f32 v130, v132, v133
	v_cvt_pk_bf16_f32 v131, v134, v135
	global_store_dwordx4 v[138:139], v[128:131], off offset:256 sc1 nt
	v_mov_b64_e32 v[134:135], v[74:75]
	s_and_b64 vcc, exec, s[38:39]
	v_mov_b64_e32 v[130:131], v[78:79]
	v_mov_b64_e32 v[128:129], v[76:77]
	v_mov_b64_e32 v[132:133], v[72:73]
	s_cbranch_vccnz .LBB0_367
	v_mul_f32_e32 v129, 0xbfb8aa3b, v72
	v_mul_f32_e32 v130, 0xbfb8aa3b, v77
	v_exp_f32_e32 v129, v129
	v_exp_f32_e32 v130, v130
	v_mul_f32_e32 v131, 0xbfb8aa3b, v78
	v_mul_f32_e32 v133, 0xbfb8aa3b, v74
	v_add_f32_e32 v129, 1.0, v129
	v_rcp_f32_e32 v132, v129
	v_add_f32_e32 v129, 1.0, v130
	v_mul_f32_e32 v130, 0xbfb8aa3b, v73
	v_exp_f32_e32 v130, v130
	v_exp_f32_e32 v131, v131
	v_exp_f32_e32 v133, v133
	v_mul_f32_e32 v128, 0xbfb8aa3b, v76
	v_add_f32_e32 v138, 1.0, v130
	v_add_f32_e32 v130, 1.0, v131
	v_add_f32_e32 v131, 1.0, v133
	v_mul_f32_e32 v133, 0xbfb8aa3b, v79
	v_mul_f32_e32 v134, 0xbfb8aa3b, v75
	v_exp_f32_e32 v128, v128
	v_exp_f32_e32 v133, v133
	v_exp_f32_e32 v135, v134
	v_rcp_f32_e32 v134, v131
	v_add_f32_e32 v128, 1.0, v128
	v_add_f32_e32 v131, 1.0, v133
	v_add_f32_e32 v133, 1.0, v135
	v_rcp_f32_e32 v128, v128
	v_rcp_f32_e32 v129, v129
	v_rcp_f32_e32 v130, v130
	v_rcp_f32_e32 v131, v131
	v_rcp_f32_e32 v135, v133
	v_rcp_f32_e32 v133, v138
	v_pk_mul_f32 v[128:129], v[76:77], v[128:129]
	v_pk_mul_f32 v[130:131], v[78:79], v[130:131]
	v_pk_mul_f32 v[134:135], v[74:75], v[134:135]
	v_pk_mul_f32 v[132:133], v[72:73], v[132:133]
; __device__ __forceinline__ unsigned cvt_pk_bf16(float lo, float hi) { f32x2_t v = {lo, hi}; bf16x2_t r = __builtin_convertvector(v, bf16x2_t); return __builtin_bit_cast(unsigned, r); }
; __device__ __forceinline__ float sigmoidf_(float v) { return __builtin_amdgcn_rcpf(1.0f + __builtin_amdgcn_exp2f(-1.4426950408889634f * v)); }
;     __device__ __forceinline__ void operator()(const f32x4 (&acc)[2][2][4][2], const Unit& u, int wr, int wc, int fr, int fq) const {
;     ...
; #pragma unroll
;         for (int ai = 0; ai < 2; ++ai)
; #pragma unroll
;             for (int m = 0; m < 4; ++m) { bf16_t* rowp = O + (size_t)(row0 + ai * HALF + m * 16) * NIN + col0;
; #pragma unroll
;                 for (int bj = 0; bj < 2; ++bj) { f32x4 v0 = acc[ai][bj][m][0], v1 = acc[ai][bj][m][1];
;                     if (mode != 0) {
; #pragma unroll
;                         for (int j = 0; j < 4; ++j) { v0[j] *= sigmoidf_(v0[j]); v1[j] *= sigmoidf_(v1[j]); }
;                     }
;                     u32x4 w; w.x = cvt_pk_bf16(v0[0], v0[1]); w.y = cvt_pk_bf16(v0[2], v0[3]); w.z = cvt_pk_bf16(v1[0], v1[1]); w.w = cvt_pk_bf16(v1[2], v1[3]);
;                     *(u32x4*)(rowp + bj * HALF) = w; } }
.LBB0_367:
	v_add_u32_e32 v142, 48, v141
	v_mov_b64_e32 v[138:139], s[4:5]
	v_mad_i64_i32 v[138:139], s[2:3], v142, s14, v[138:139]
	v_lshl_add_u64 v[138:139], v[136:137], 1, v[138:139]
	v_cvt_pk_bf16_f32 v128, v128, v129
	v_cvt_pk_bf16_f32 v129, v130, v131
	v_cvt_pk_bf16_f32 v130, v132, v133
	v_cvt_pk_bf16_f32 v131, v134, v135
	global_store_dwordx4 v[138:139], v[128:131], off sc1 nt
	v_mov_b64_e32 v[134:135], v[66:67]
	s_and_b64 vcc, exec, s[38:39]
	v_mov_b64_e32 v[130:131], v[70:71]
	v_mov_b64_e32 v[128:129], v[68:69]
	v_mov_b64_e32 v[132:133], v[64:65]
	s_cbranch_vccnz .LBB0_369
	v_mul_f32_e32 v129, 0xbfb8aa3b, v64
	v_mul_f32_e32 v130, 0xbfb8aa3b, v69
	v_exp_f32_e32 v129, v129
	v_exp_f32_e32 v130, v130
	v_mul_f32_e32 v131, 0xbfb8aa3b, v70
	v_mul_f32_e32 v133, 0xbfb8aa3b, v66
	v_add_f32_e32 v129, 1.0, v129
	v_rcp_f32_e32 v132, v129
	v_add_f32_e32 v129, 1.0, v130
	v_mul_f32_e32 v130, 0xbfb8aa3b, v65
	v_exp_f32_e32 v130, v130
	v_exp_f32_e32 v131, v131
	v_exp_f32_e32 v133, v133
	v_mul_f32_e32 v128, 0xbfb8aa3b, v68
	v_add_f32_e32 v142, 1.0, v130
	v_add_f32_e32 v130, 1.0, v131
	v_add_f32_e32 v131, 1.0, v133
	v_mul_f32_e32 v133, 0xbfb8aa3b, v71
	v_mul_f32_e32 v134, 0xbfb8aa3b, v67
	v_exp_f32_e32 v128, v128
	v_exp_f32_e32 v133, v133
	v_exp_f32_e32 v135, v134
	v_rcp_f32_e32 v134, v131
	v_add_f32_e32 v128, 1.0, v128
	v_add_f32_e32 v131, 1.0, v133
	v_add_f32_e32 v133, 1.0, v135
	v_rcp_f32_e32 v128, v128
	v_rcp_f32_e32 v129, v129
	v_rcp_f32_e32 v130, v130
	v_rcp_f32_e32 v131, v131
	v_rcp_f32_e32 v135, v133
	v_rcp_f32_e32 v133, v142
	v_pk_mul_f32 v[128:129], v[68:69], v[128:129]
	v_pk_mul_f32 v[130:131], v[70:71], v[130:131]
	v_pk_mul_f32 v[134:135], v[66:67], v[134:135]
	v_pk_mul_f32 v[132:133], v[64:65], v[132:133]
.LBB0_369:
	v_cvt_pk_bf16_f32 v128, v128, v129
	v_cvt_pk_bf16_f32 v129, v130, v131
	v_cvt_pk_bf16_f32 v130, v132, v133
	v_cvt_pk_bf16_f32 v131, v134, v135
	global_store_dwordx4 v[138:139], v[128:131], off offset:256 sc1 nt
	v_mov_b64_e32 v[134:135], v[58:59]
	s_and_b64 vcc, exec, s[38:39]
	v_mov_b64_e32 v[130:131], v[62:63]
	v_mov_b64_e32 v[128:129], v[60:61]
	v_mov_b64_e32 v[132:133], v[56:57]
	s_cbranch_vccnz .LBB0_371
	v_mul_f32_e32 v129, 0xbfb8aa3b, v56
	v_mul_f32_e32 v130, 0xbfb8aa3b, v61
	v_exp_f32_e32 v129, v129
	v_exp_f32_e32 v130, v130
	v_mul_f32_e32 v131, 0xbfb8aa3b, v62
	v_mul_f32_e32 v133, 0xbfb8aa3b, v58
	v_add_f32_e32 v129, 1.0, v129
	v_rcp_f32_e32 v132, v129
	v_add_f32_e32 v129, 1.0, v130
	v_mul_f32_e32 v130, 0xbfb8aa3b, v57
	v_exp_f32_e32 v130, v130
	v_exp_f32_e32 v131, v131
	v_exp_f32_e32 v133, v133
	v_mul_f32_e32 v128, 0xbfb8aa3b, v60
	v_add_f32_e32 v138, 1.0, v130
	v_add_f32_e32 v130, 1.0, v131
	v_add_f32_e32 v131, 1.0, v133
	v_mul_f32_e32 v133, 0xbfb8aa3b, v63
	v_mul_f32_e32 v134, 0xbfb8aa3b, v59
	v_exp_f32_e32 v128, v128
	v_exp_f32_e32 v133, v133
	v_exp_f32_e32 v135, v134
	v_rcp_f32_e32 v134, v131
	v_add_f32_e32 v128, 1.0, v128
	v_add_f32_e32 v131, 1.0, v133
	v_add_f32_e32 v133, 1.0, v135
	v_rcp_f32_e32 v128, v128
	v_rcp_f32_e32 v129, v129
	v_rcp_f32_e32 v130, v130
	v_rcp_f32_e32 v131, v131
	v_rcp_f32_e32 v135, v133
	v_rcp_f32_e32 v133, v138
	v_pk_mul_f32 v[128:129], v[60:61], v[128:129]
	v_pk_mul_f32 v[130:131], v[62:63], v[130:131]
	v_pk_mul_f32 v[134:135], v[58:59], v[134:135]
	v_pk_mul_f32 v[132:133], v[56:57], v[132:133]
.LBB0_371:
	v_add_u32_e32 v142, 0x80, v141
	v_mov_b64_e32 v[138:139], s[4:5]
	v_mad_i64_i32 v[138:139], s[2:3], v142, s14, v[138:139]
	v_lshl_add_u64 v[138:139], v[136:137], 1, v[138:139]
	v_cvt_pk_bf16_f32 v128, v128, v129
	v_cvt_pk_bf16_f32 v129, v130, v131
	v_cvt_pk_bf16_f32 v130, v132, v133
	v_cvt_pk_bf16_f32 v131, v134, v135
	global_store_dwordx4 v[138:139], v[128:131], off sc1 nt
	v_mov_b64_e32 v[134:135], v[50:51]
	s_and_b64 vcc, exec, s[38:39]
	v_mov_b64_e32 v[130:131], v[54:55]
	v_mov_b64_e32 v[128:129], v[52:53]
	v_mov_b64_e32 v[132:133], v[48:49]
	s_cbranch_vccnz .LBB0_373
	v_mul_f32_e32 v129, 0xbfb8aa3b, v48
	v_mul_f32_e32 v130, 0xbfb8aa3b, v53
	v_exp_f32_e32 v129, v129
	v_exp_f32_e32 v130, v130
	v_mul_f32_e32 v131, 0xbfb8aa3b, v54
	v_mul_f32_e32 v133, 0xbfb8aa3b, v50
	v_add_f32_e32 v129, 1.0, v129
	v_rcp_f32_e32 v132, v129
	v_add_f32_e32 v129, 1.0, v130
	v_mul_f32_e32 v130, 0xbfb8aa3b, v49
	v_exp_f32_e32 v130, v130
	v_exp_f32_e32 v131, v131
	v_exp_f32_e32 v133, v133
	v_mul_f32_e32 v128, 0xbfb8aa3b, v52
	v_add_f32_e32 v142, 1.0, v130
	v_add_f32_e32 v130, 1.0, v131
	v_add_f32_e32 v131, 1.0, v133
	v_mul_f32_e32 v133, 0xbfb8aa3b, v55
	v_mul_f32_e32 v134, 0xbfb8aa3b, v51
	v_exp_f32_e32 v128, v128
	v_exp_f32_e32 v133, v133
	v_exp_f32_e32 v135, v134
	v_rcp_f32_e32 v134, v131
	v_add_f32_e32 v128, 1.0, v128
	v_add_f32_e32 v131, 1.0, v133
	v_add_f32_e32 v133, 1.0, v135
	v_rcp_f32_e32 v128, v128
	v_rcp_f32_e32 v129, v129
	v_rcp_f32_e32 v130, v130
	v_rcp_f32_e32 v131, v131
	v_rcp_f32_e32 v135, v133
	v_rcp_f32_e32 v133, v142
	v_pk_mul_f32 v[128:129], v[52:53], v[128:129]
	v_pk_mul_f32 v[130:131], v[54:55], v[130:131]
	v_pk_mul_f32 v[134:135], v[50:51], v[134:135]
	v_pk_mul_f32 v[132:133], v[48:49], v[132:133]
; __device__ __forceinline__ unsigned cvt_pk_bf16(float lo, float hi) { f32x2_t v = {lo, hi}; bf16x2_t r = __builtin_convertvector(v, bf16x2_t); return __builtin_bit_cast(unsigned, r); }
; __device__ __forceinline__ float sigmoidf_(float v) { return __builtin_amdgcn_rcpf(1.0f + __builtin_amdgcn_exp2f(-1.4426950408889634f * v)); }
;     __device__ __forceinline__ void operator()(const f32x4 (&acc)[2][2][4][2], const Unit& u, int wr, int wc, int fr, int fq) const {
;     ...
; #pragma unroll
;         for (int ai = 0; ai < 2; ++ai)
; #pragma unroll
;             for (int m = 0; m < 4; ++m) { bf16_t* rowp = O + (size_t)(row0 + ai * HALF + m * 16) * NIN + col0;
; #pragma unroll
;                 for (int bj = 0; bj < 2; ++bj) { f32x4 v0 = acc[ai][bj][m][0], v1 = acc[ai][bj][m][1];
;                     if (mode != 0) {
; #pragma unroll
;                         for (int j = 0; j < 4; ++j) { v0[j] *= sigmoidf_(v0[j]); v1[j] *= sigmoidf_(v1[j]); }
;                     }
;                     u32x4 w; w.x = cvt_pk_bf16(v0[0], v0[1]); w.y = cvt_pk_bf16(v0[2], v0[3]); w.z = cvt_pk_bf16(v1[0], v1[1]); w.w = cvt_pk_bf16(v1[2], v1[3]);
;                     *(u32x4*)(rowp + bj * HALF) = w; } }
.LBB0_373:
	v_cvt_pk_bf16_f32 v128, v128, v129
	v_cvt_pk_bf16_f32 v129, v130, v131
	v_cvt_pk_bf16_f32 v130, v132, v133
	v_cvt_pk_bf16_f32 v131, v134, v135
	global_store_dwordx4 v[138:139], v[128:131], off offset:256 sc1 nt
	v_mov_b64_e32 v[134:135], v[42:43]
	s_and_b64 vcc, exec, s[38:39]
	v_mov_b64_e32 v[130:131], v[46:47]
	v_mov_b64_e32 v[128:129], v[44:45]
	v_mov_b64_e32 v[132:133], v[40:41]
	s_cbranch_vccnz .LBB0_375
	v_mul_f32_e32 v129, 0xbfb8aa3b, v40
	v_mul_f32_e32 v130, 0xbfb8aa3b, v45
	v_exp_f32_e32 v129, v129
	v_exp_f32_e32 v130, v130
	v_mul_f32_e32 v131, 0xbfb8aa3b, v46
	v_mul_f32_e32 v133, 0xbfb8aa3b, v42
	v_add_f32_e32 v129, 1.0, v129
	v_rcp_f32_e32 v132, v129
	v_add_f32_e32 v129, 1.0, v130
	v_mul_f32_e32 v130, 0xbfb8aa3b, v41
	v_exp_f32_e32 v130, v130
	v_exp_f32_e32 v131, v131
	v_exp_f32_e32 v133, v133
	v_mul_f32_e32 v128, 0xbfb8aa3b, v44
	v_add_f32_e32 v138, 1.0, v130
	v_add_f32_e32 v130, 1.0, v131
	v_add_f32_e32 v131, 1.0, v133
	v_mul_f32_e32 v133, 0xbfb8aa3b, v47
	v_mul_f32_e32 v134, 0xbfb8aa3b, v43
	v_exp_f32_e32 v128, v128
	v_exp_f32_e32 v133, v133
	v_exp_f32_e32 v135, v134
	v_rcp_f32_e32 v134, v131
	v_add_f32_e32 v128, 1.0, v128
	v_add_f32_e32 v131, 1.0, v133
	v_add_f32_e32 v133, 1.0, v135
	v_rcp_f32_e32 v128, v128
	v_rcp_f32_e32 v129, v129
	v_rcp_f32_e32 v130, v130
	v_rcp_f32_e32 v131, v131
	v_rcp_f32_e32 v135, v133
	v_rcp_f32_e32 v133, v138
	v_pk_mul_f32 v[128:129], v[44:45], v[128:129]
	v_pk_mul_f32 v[130:131], v[46:47], v[130:131]
	v_pk_mul_f32 v[134:135], v[42:43], v[134:135]
	v_pk_mul_f32 v[132:133], v[40:41], v[132:133]
.LBB0_375:
	v_add_u32_e32 v142, 0x90, v141
	v_mov_b64_e32 v[138:139], s[4:5]
	v_mad_i64_i32 v[138:139], s[2:3], v142, s14, v[138:139]
	v_lshl_add_u64 v[138:139], v[136:137], 1, v[138:139]
	v_cvt_pk_bf16_f32 v128, v128, v129
	v_cvt_pk_bf16_f32 v129, v130, v131
	v_cvt_pk_bf16_f32 v130, v132, v133
	v_cvt_pk_bf16_f32 v131, v134, v135
	global_store_dwordx4 v[138:139], v[128:131], off sc1 nt
	v_mov_b64_e32 v[134:135], v[34:35]
	s_and_b64 vcc, exec, s[38:39]
	v_mov_b64_e32 v[130:131], v[38:39]
	v_mov_b64_e32 v[128:129], v[36:37]
	v_mov_b64_e32 v[132:133], v[32:33]
	s_cbranch_vccnz .LBB0_377
	v_mul_f32_e32 v129, 0xbfb8aa3b, v32
	v_mul_f32_e32 v130, 0xbfb8aa3b, v37
	v_exp_f32_e32 v129, v129
	v_exp_f32_e32 v130, v130
	v_mul_f32_e32 v131, 0xbfb8aa3b, v38
	v_mul_f32_e32 v133, 0xbfb8aa3b, v34
	v_add_f32_e32 v129, 1.0, v129
	v_rcp_f32_e32 v132, v129
	v_add_f32_e32 v129, 1.0, v130
	v_mul_f32_e32 v130, 0xbfb8aa3b, v33
	v_exp_f32_e32 v130, v130
	v_exp_f32_e32 v131, v131
	v_exp_f32_e32 v133, v133
	v_mul_f32_e32 v128, 0xbfb8aa3b, v36
	v_add_f32_e32 v142, 1.0, v130
	v_add_f32_e32 v130, 1.0, v131
	v_add_f32_e32 v131, 1.0, v133
	v_mul_f32_e32 v133, 0xbfb8aa3b, v39
	v_mul_f32_e32 v134, 0xbfb8aa3b, v35
	v_exp_f32_e32 v128, v128
	v_exp_f32_e32 v133, v133
	v_exp_f32_e32 v135, v134
	v_rcp_f32_e32 v134, v131
	v_add_f32_e32 v128, 1.0, v128
	v_add_f32_e32 v131, 1.0, v133
	v_add_f32_e32 v133, 1.0, v135
	v_rcp_f32_e32 v128, v128
	v_rcp_f32_e32 v129, v129
	v_rcp_f32_e32 v130, v130
	v_rcp_f32_e32 v131, v131
	v_rcp_f32_e32 v135, v133
	v_rcp_f32_e32 v133, v142
	v_pk_mul_f32 v[128:129], v[36:37], v[128:129]
	v_pk_mul_f32 v[130:131], v[38:39], v[130:131]
	v_pk_mul_f32 v[134:135], v[34:35], v[134:135]
	v_pk_mul_f32 v[132:133], v[32:33], v[132:133]
.LBB0_377:
	v_cvt_pk_bf16_f32 v128, v128, v129
	v_cvt_pk_bf16_f32 v129, v130, v131
	v_cvt_pk_bf16_f32 v130, v132, v133
	v_cvt_pk_bf16_f32 v131, v134, v135
	global_store_dwordx4 v[138:139], v[128:131], off offset:256 sc1 nt
	v_mov_b64_e32 v[134:135], v[26:27]
	s_and_b64 vcc, exec, s[38:39]
	v_mov_b64_e32 v[130:131], v[30:31]
	v_mov_b64_e32 v[128:129], v[28:29]
	v_mov_b64_e32 v[132:133], v[24:25]
	s_cbranch_vccnz .LBB0_379
	v_mul_f32_e32 v129, 0xbfb8aa3b, v24
	v_mul_f32_e32 v130, 0xbfb8aa3b, v29
	v_exp_f32_e32 v129, v129
	v_exp_f32_e32 v130, v130
	v_mul_f32_e32 v131, 0xbfb8aa3b, v30
	v_mul_f32_e32 v133, 0xbfb8aa3b, v26
	v_add_f32_e32 v129, 1.0, v129
	v_rcp_f32_e32 v132, v129
	v_add_f32_e32 v129, 1.0, v130
	v_mul_f32_e32 v130, 0xbfb8aa3b, v25
	v_exp_f32_e32 v130, v130
	v_exp_f32_e32 v131, v131
	v_exp_f32_e32 v133, v133
	v_mul_f32_e32 v128, 0xbfb8aa3b, v28
	v_add_f32_e32 v138, 1.0, v130
	v_add_f32_e32 v130, 1.0, v131
	v_add_f32_e32 v131, 1.0, v133
	v_mul_f32_e32 v133, 0xbfb8aa3b, v31
	v_mul_f32_e32 v134, 0xbfb8aa3b, v27
	v_exp_f32_e32 v128, v128
	v_exp_f32_e32 v133, v133
	v_exp_f32_e32 v135, v134
	v_rcp_f32_e32 v134, v131
	v_add_f32_e32 v128, 1.0, v128
	v_add_f32_e32 v131, 1.0, v133
	v_add_f32_e32 v133, 1.0, v135
	v_rcp_f32_e32 v128, v128
	v_rcp_f32_e32 v129, v129
	v_rcp_f32_e32 v130, v130
	v_rcp_f32_e32 v131, v131
	v_rcp_f32_e32 v135, v133
	v_rcp_f32_e32 v133, v138
	v_pk_mul_f32 v[128:129], v[28:29], v[128:129]
	v_pk_mul_f32 v[130:131], v[30:31], v[130:131]
	v_pk_mul_f32 v[134:135], v[26:27], v[134:135]
	v_pk_mul_f32 v[132:133], v[24:25], v[132:133]
; __device__ __forceinline__ unsigned cvt_pk_bf16(float lo, float hi) { f32x2_t v = {lo, hi}; bf16x2_t r = __builtin_convertvector(v, bf16x2_t); return __builtin_bit_cast(unsigned, r); }
; __device__ __forceinline__ float sigmoidf_(float v) { return __builtin_amdgcn_rcpf(1.0f + __builtin_amdgcn_exp2f(-1.4426950408889634f * v)); }
;     __device__ __forceinline__ void operator()(const f32x4 (&acc)[2][2][4][2], const Unit& u, int wr, int wc, int fr, int fq) const {
;     ...
; #pragma unroll
;         for (int ai = 0; ai < 2; ++ai)
; #pragma unroll
;             for (int m = 0; m < 4; ++m) { bf16_t* rowp = O + (size_t)(row0 + ai * HALF + m * 16) * NIN + col0;
; #pragma unroll
;                 for (int bj = 0; bj < 2; ++bj) { f32x4 v0 = acc[ai][bj][m][0], v1 = acc[ai][bj][m][1];
;                     if (mode != 0) {
; #pragma unroll
;                         for (int j = 0; j < 4; ++j) { v0[j] *= sigmoidf_(v0[j]); v1[j] *= sigmoidf_(v1[j]); }
;                     }
;                     u32x4 w; w.x = cvt_pk_bf16(v0[0], v0[1]); w.y = cvt_pk_bf16(v0[2], v0[3]); w.z = cvt_pk_bf16(v1[0], v1[1]); w.w = cvt_pk_bf16(v1[2], v1[3]);
;                     *(u32x4*)(rowp + bj * HALF) = w; } }
.LBB0_379:
	v_add_u32_e32 v142, 0xa0, v141
	v_mov_b64_e32 v[138:139], s[4:5]
	v_mad_i64_i32 v[138:139], s[2:3], v142, s14, v[138:139]
	v_lshl_add_u64 v[138:139], v[136:137], 1, v[138:139]
	v_cvt_pk_bf16_f32 v128, v128, v129
	v_cvt_pk_bf16_f32 v129, v130, v131
	v_cvt_pk_bf16_f32 v130, v132, v133
	v_cvt_pk_bf16_f32 v131, v134, v135
	global_store_dwordx4 v[138:139], v[128:131], off sc1 nt
	v_mov_b64_e32 v[134:135], v[18:19]
	s_and_b64 vcc, exec, s[38:39]
	v_mov_b64_e32 v[130:131], v[22:23]
	v_mov_b64_e32 v[128:129], v[20:21]
	v_mov_b64_e32 v[132:133], v[16:17]
	s_cbranch_vccnz .LBB0_381
	v_mul_f32_e32 v129, 0xbfb8aa3b, v16
	v_mul_f32_e32 v130, 0xbfb8aa3b, v21
	v_exp_f32_e32 v129, v129
	v_exp_f32_e32 v130, v130
	v_mul_f32_e32 v131, 0xbfb8aa3b, v22
	v_mul_f32_e32 v133, 0xbfb8aa3b, v18
	v_add_f32_e32 v129, 1.0, v129
	v_rcp_f32_e32 v132, v129
	v_add_f32_e32 v129, 1.0, v130
	v_mul_f32_e32 v130, 0xbfb8aa3b, v17
	v_exp_f32_e32 v130, v130
	v_exp_f32_e32 v131, v131
	v_exp_f32_e32 v133, v133
	v_mul_f32_e32 v128, 0xbfb8aa3b, v20
	v_add_f32_e32 v142, 1.0, v130
	v_add_f32_e32 v130, 1.0, v131
	v_add_f32_e32 v131, 1.0, v133
	v_mul_f32_e32 v133, 0xbfb8aa3b, v23
	v_mul_f32_e32 v134, 0xbfb8aa3b, v19
	v_exp_f32_e32 v128, v128
	v_exp_f32_e32 v133, v133
	v_exp_f32_e32 v135, v134
	v_rcp_f32_e32 v134, v131
	v_add_f32_e32 v128, 1.0, v128
	v_add_f32_e32 v131, 1.0, v133
	v_add_f32_e32 v133, 1.0, v135
	v_rcp_f32_e32 v128, v128
	v_rcp_f32_e32 v129, v129
	v_rcp_f32_e32 v130, v130
	v_rcp_f32_e32 v131, v131
	v_rcp_f32_e32 v135, v133
	v_rcp_f32_e32 v133, v142
	v_pk_mul_f32 v[128:129], v[20:21], v[128:129]
	v_pk_mul_f32 v[130:131], v[22:23], v[130:131]
	v_pk_mul_f32 v[134:135], v[18:19], v[134:135]
	v_pk_mul_f32 v[132:133], v[16:17], v[132:133]
.LBB0_381:
	v_cvt_pk_bf16_f32 v128, v128, v129
	v_cvt_pk_bf16_f32 v129, v130, v131
	v_cvt_pk_bf16_f32 v130, v132, v133
	v_cvt_pk_bf16_f32 v131, v134, v135
	global_store_dwordx4 v[138:139], v[128:131], off offset:256 sc1 nt
	v_mov_b64_e32 v[134:135], v[10:11]
	s_and_b64 vcc, exec, s[38:39]
	v_mov_b64_e32 v[130:131], v[14:15]
	v_mov_b64_e32 v[128:129], v[12:13]
	v_mov_b64_e32 v[132:133], v[8:9]
	s_cbranch_vccnz .LBB0_383
	v_mul_f32_e32 v129, 0xbfb8aa3b, v8
	v_mul_f32_e32 v130, 0xbfb8aa3b, v13
	v_exp_f32_e32 v129, v129
	v_exp_f32_e32 v130, v130
	v_mul_f32_e32 v131, 0xbfb8aa3b, v14
	v_mul_f32_e32 v133, 0xbfb8aa3b, v10
	v_add_f32_e32 v129, 1.0, v129
	v_rcp_f32_e32 v132, v129
	v_add_f32_e32 v129, 1.0, v130
	v_mul_f32_e32 v130, 0xbfb8aa3b, v9
	v_exp_f32_e32 v130, v130
	v_exp_f32_e32 v131, v131
	v_exp_f32_e32 v133, v133
	v_mul_f32_e32 v128, 0xbfb8aa3b, v12
	v_add_f32_e32 v138, 1.0, v130
	v_add_f32_e32 v130, 1.0, v131
	v_add_f32_e32 v131, 1.0, v133
	v_mul_f32_e32 v133, 0xbfb8aa3b, v15
	v_mul_f32_e32 v134, 0xbfb8aa3b, v11
	v_exp_f32_e32 v128, v128
	v_exp_f32_e32 v133, v133
	v_exp_f32_e32 v135, v134
	v_rcp_f32_e32 v134, v131
	v_add_f32_e32 v128, 1.0, v128
	v_add_f32_e32 v131, 1.0, v133
	v_add_f32_e32 v133, 1.0, v135
	v_rcp_f32_e32 v128, v128
	v_rcp_f32_e32 v129, v129
	v_rcp_f32_e32 v130, v130
	v_rcp_f32_e32 v131, v131
	v_rcp_f32_e32 v135, v133
	v_rcp_f32_e32 v133, v138
	v_pk_mul_f32 v[128:129], v[12:13], v[128:129]
	v_pk_mul_f32 v[130:131], v[14:15], v[130:131]
	v_pk_mul_f32 v[134:135], v[10:11], v[134:135]
	v_pk_mul_f32 v[132:133], v[8:9], v[132:133]
.LBB0_383:
	v_add_u32_e32 v141, 0xb0, v141
	v_mov_b64_e32 v[138:139], s[4:5]
	v_mad_i64_i32 v[138:139], s[2:3], v141, s14, v[138:139]
	v_lshl_add_u64 v[138:139], v[136:137], 1, v[138:139]
	v_cvt_pk_bf16_f32 v128, v128, v129
	v_cvt_pk_bf16_f32 v129, v130, v131
	v_cvt_pk_bf16_f32 v130, v132, v133
	v_cvt_pk_bf16_f32 v131, v134, v135
	global_store_dwordx4 v[138:139], v[128:131], off sc1 nt
	v_mov_b64_e32 v[134:135], v[2:3]
	s_and_b64 vcc, exec, s[38:39]
	v_mov_b64_e32 v[130:131], v[6:7]
	v_mov_b64_e32 v[128:129], v[4:5]
	v_mov_b64_e32 v[132:133], v[0:1]
	s_cbranch_vccnz .LBB0_385
	v_mul_f32_e32 v129, 0xbfb8aa3b, v0
	v_mul_f32_e32 v130, 0xbfb8aa3b, v5
	v_exp_f32_e32 v129, v129
	v_exp_f32_e32 v130, v130
	v_mul_f32_e32 v131, 0xbfb8aa3b, v6
	v_mul_f32_e32 v133, 0xbfb8aa3b, v2
	v_add_f32_e32 v129, 1.0, v129
	v_rcp_f32_e32 v132, v129
	v_add_f32_e32 v129, 1.0, v130
	v_mul_f32_e32 v130, 0xbfb8aa3b, v1
	v_exp_f32_e32 v130, v130
	v_exp_f32_e32 v131, v131
	v_exp_f32_e32 v133, v133
	v_mul_f32_e32 v128, 0xbfb8aa3b, v4
	v_add_f32_e32 v137, 1.0, v130
	v_add_f32_e32 v130, 1.0, v131
	v_add_f32_e32 v131, 1.0, v133
	v_mul_f32_e32 v133, 0xbfb8aa3b, v7
	v_mul_f32_e32 v134, 0xbfb8aa3b, v3
	v_exp_f32_e32 v128, v128
	v_exp_f32_e32 v133, v133
	v_exp_f32_e32 v135, v134
	v_rcp_f32_e32 v134, v131
	v_add_f32_e32 v128, 1.0, v128
	v_add_f32_e32 v131, 1.0, v133
	v_add_f32_e32 v133, 1.0, v135
	v_rcp_f32_e32 v128, v128
	v_rcp_f32_e32 v129, v129
	v_rcp_f32_e32 v130, v130
	v_rcp_f32_e32 v131, v131
	v_rcp_f32_e32 v135, v133
	v_rcp_f32_e32 v133, v137
	v_pk_mul_f32 v[128:129], v[4:5], v[128:129]
	v_pk_mul_f32 v[130:131], v[6:7], v[130:131]
	v_pk_mul_f32 v[134:135], v[2:3], v[134:135]
	v_pk_mul_f32 v[132:133], v[0:1], v[132:133]
.LBB0_385:
	v_cvt_pk_bf16_f32 v128, v128, v129
	v_cvt_pk_bf16_f32 v129, v130, v131
	v_cvt_pk_bf16_f32 v130, v132, v133
	v_cvt_pk_bf16_f32 v131, v134, v135
	global_store_dwordx4 v[138:139], v[128:131], off offset:256 sc1 nt
	s_branch .LBB0_352
; #define LAS __attribute__((address_space(3)))
; __device__ __forceinline__ unsigned cvt_pk_bf16(float lo, float hi) { f32x2_t v = {lo, hi}; bf16x2_t r = __builtin_convertvector(v, bf16x2_t); return __builtin_bit_cast(unsigned, r); }
; __device__ __forceinline__ float sigmoidf_(float v) { return __builtin_amdgcn_rcpf(1.0f + __builtin_amdgcn_exp2f(-1.4426950408889634f * v)); }
;     __device__ __forceinline__ void operator()(const f32x4 (&acc)[2][2][4][2], const Unit& u, int wr, int wc, int fr, int fq) const {
;     ...
;         if (mode == 2) {
;             const int gt = u.pn - C_G / BM;
;             u32x4* gf = GF + ((size_t)(((gt >> 3) * 64 + u.pm) * 8 + (gt & 7)) * 8 + (wr * 4 + wc)) * 1024 + fq * 16 + fr;
;             f32x4 bv[2][2];
; #pragma unroll
;             for (int bj = 0; bj < 2; ++bj)
; #pragma unroll
;                 for (int n = 0; n < 2; ++n) bv[bj][n] = *(const LAS f32x4*)(bgate + (col0 - C_G) + bj * HALF + 4 * n);
; #pragma unroll
;             for (int ai = 0; ai < 2; ++ai)
; #pragma unroll
;                 for (int m = 0; m < 4; ++m)
; #pragma unroll
;                     for (int bj = 0; bj < 2; ++bj) { const f32x4 v0 = acc[ai][bj][m][0] + bv[bj][0], v1 = acc[ai][bj][m][1] + bv[bj][1];
;                         u32x4 w; w.x = cvt_pk_bf16(sigmoidf_(v0[0]), sigmoidf_(v0[1])); w.y = cvt_pk_bf16(sigmoidf_(v0[2]), sigmoidf_(v0[3]));
;                         w.z = cvt_pk_bf16(sigmoidf_(v1[0]), sigmoidf_(v1[1])); w.w = cvt_pk_bf16(sigmoidf_(v1[2]), sigmoidf_(v1[3]));
;                         gf[((ai * 4 + m) * 2 + bj) * 64] = w; }
;             return;
.LBB0_386:
	v_readlane_b32 s11, v251, 11
	v_lshlrev_b32_e32 v160, 4, v140
	s_sub_i32 s2, s46, 46
	v_lshl_add_u32 v128, v136, 2, s11
	v_add_u32_e32 v129, 0xffff4800, v128
	v_add_u32_e32 v130, 0xffff4810, v128
	ds_read_b128 v[140:143], v129
	ds_read_b128 v[136:139], v130
	s_lshl_b32 s3, s2, 3
	s_and_b32 s3, s3, 0x1fffffc0
	s_add_i32 s3, s3, s44
	s_lshl_b32 s3, s3, 3
	s_and_b32 s2, s2, 7
	s_waitcnt lgkmcnt(0)
	v_pk_add_f32 v[120:121], v[120:121], v[136:137]
	s_or_b32 s2, s3, s2
	v_mul_f32_e32 v120, 0xbfb8aa3b, v120
	s_ashr_i32 s3, s2, 31
	v_exp_f32_e32 v120, v120
	v_mul_f32_e32 v121, 0xbfb8aa3b, v121
	s_lshl_b64 s[2:3], s[2:3], 17
	v_exp_f32_e32 v121, v121
	s_add_u32 s2, s60, s2
	v_ashrrev_i32_e32 v161, 31, v160
	s_addc_u32 s3, s61, s3
	v_ashrrev_i32_e32 v155, 31, v154
	v_add_u32_e32 v129, 0xffff4a00, v128
	v_add_u32_e32 v128, 0xffff4a10, v128
	v_lshl_add_u64 v[160:161], v[160:161], 4, s[2:3]
	v_pk_add_f32 v[122:123], v[122:123], v[138:139]
	v_add_f32_e32 v120, 1.0, v120
	ds_read_b128 v[132:135], v129
	ds_read_b128 v[128:131], v128
	v_lshl_add_u64 v[154:155], v[154:155], 4, v[160:161]
	v_pk_add_f32 v[126:127], v[126:127], v[142:143]
	v_pk_add_f32 v[124:125], v[124:125], v[140:141]
	v_rcp_f32_e32 v160, v120
	v_add_f32_e32 v120, 1.0, v121
	v_mul_f32_e32 v121, 0xbfb8aa3b, v122
	v_mul_f32_e32 v124, 0xbfb8aa3b, v124
	v_mul_f32_e32 v125, 0xbfb8aa3b, v125
	v_mul_f32_e32 v126, 0xbfb8aa3b, v126
	v_mul_f32_e32 v127, 0xbfb8aa3b, v127
	v_exp_f32_e32 v121, v121
	v_mul_f32_e32 v122, 0xbfb8aa3b, v123
	v_exp_f32_e32 v124, v124
	v_exp_f32_e32 v125, v125
	v_exp_f32_e32 v126, v126
	v_exp_f32_e32 v127, v127
	v_exp_f32_e32 v122, v122
	v_rcp_f32_e32 v123, v120
	v_add_f32_e32 v120, 1.0, v121
	s_waitcnt lgkmcnt(0)
	v_pk_add_f32 v[112:113], v[112:113], v[128:129]
	v_add_f32_e32 v124, 1.0, v124
	v_add_f32_e32 v125, 1.0, v125
	v_add_f32_e32 v126, 1.0, v126
	v_add_f32_e32 v127, 1.0, v127
	v_rcp_f32_e32 v161, v120
	v_add_f32_e32 v120, 1.0, v122
	v_mul_f32_e32 v112, 0xbfb8aa3b, v112
	v_rcp_f32_e32 v124, v124
	v_rcp_f32_e32 v125, v125
	v_rcp_f32_e32 v126, v126
	v_rcp_f32_e32 v127, v127
	v_rcp_f32_e32 v162, v120
	v_exp_f32_e32 v112, v112
	v_mul_f32_e32 v113, 0xbfb8aa3b, v113
	v_exp_f32_e32 v113, v113
	v_cvt_pk_bf16_f32 v120, v124, v125
	v_cvt_pk_bf16_f32 v121, v126, v127
	v_cvt_pk_bf16_f32 v122, v160, v123
	v_cvt_pk_bf16_f32 v123, v161, v162
	v_pk_add_f32 v[114:115], v[114:115], v[130:131]
	v_add_f32_e32 v112, 1.0, v112
	global_store_dwordx4 v[154:155], v[120:123], off sc1 nt
	v_pk_add_f32 v[118:119], v[118:119], v[134:135]
	v_pk_add_f32 v[116:117], v[116:117], v[132:133]
	v_rcp_f32_e32 v120, v112
	v_add_f32_e32 v112, 1.0, v113
	v_mul_f32_e32 v113, 0xbfb8aa3b, v114
	v_mul_f32_e32 v116, 0xbfb8aa3b, v116
	v_mul_f32_e32 v117, 0xbfb8aa3b, v117
	v_mul_f32_e32 v118, 0xbfb8aa3b, v118
	v_mul_f32_e32 v119, 0xbfb8aa3b, v119
	v_exp_f32_e32 v113, v113
	v_mul_f32_e32 v114, 0xbfb8aa3b, v115
	v_exp_f32_e32 v116, v116
	v_exp_f32_e32 v117, v117
	v_exp_f32_e32 v118, v118
	v_exp_f32_e32 v119, v119
	v_exp_f32_e32 v114, v114
	v_rcp_f32_e32 v115, v112
	v_add_f32_e32 v112, 1.0, v113
	v_pk_add_f32 v[104:105], v[104:105], v[136:137]
	v_add_f32_e32 v116, 1.0, v116
	v_add_f32_e32 v117, 1.0, v117
	v_add_f32_e32 v118, 1.0, v118
	v_add_f32_e32 v119, 1.0, v119
	v_rcp_f32_e32 v121, v112
	v_add_f32_e32 v112, 1.0, v114
	v_mul_f32_e32 v104, 0xbfb8aa3b, v104
	v_rcp_f32_e32 v116, v116
	v_rcp_f32_e32 v117, v117
	v_rcp_f32_e32 v118, v118
	v_rcp_f32_e32 v119, v119
	v_rcp_f32_e32 v122, v112
	v_exp_f32_e32 v104, v104
	v_mul_f32_e32 v105, 0xbfb8aa3b, v105
	v_exp_f32_e32 v105, v105
	v_cvt_pk_bf16_f32 v112, v116, v117
	v_cvt_pk_bf16_f32 v113, v118, v119
	v_cvt_pk_bf16_f32 v114, v120, v115
	v_cvt_pk_bf16_f32 v115, v121, v122
	v_pk_add_f32 v[106:107], v[106:107], v[138:139]
	v_add_f32_e32 v104, 1.0, v104
	global_store_dwordx4 v[154:155], v[112:115], off offset:1024 sc1 nt
	v_pk_add_f32 v[110:111], v[110:111], v[142:143]
	v_pk_add_f32 v[108:109], v[108:109], v[140:141]
	v_rcp_f32_e32 v112, v104
	v_add_f32_e32 v104, 1.0, v105
	v_mul_f32_e32 v105, 0xbfb8aa3b, v106
	v_mul_f32_e32 v108, 0xbfb8aa3b, v108
	v_mul_f32_e32 v109, 0xbfb8aa3b, v109
	v_mul_f32_e32 v110, 0xbfb8aa3b, v110
	v_mul_f32_e32 v111, 0xbfb8aa3b, v111
	v_exp_f32_e32 v105, v105
	v_mul_f32_e32 v106, 0xbfb8aa3b, v107
	v_exp_f32_e32 v108, v108
	v_exp_f32_e32 v109, v109
	v_exp_f32_e32 v110, v110
	v_exp_f32_e32 v111, v111
	v_exp_f32_e32 v106, v106
	v_rcp_f32_e32 v107, v104
	v_add_f32_e32 v104, 1.0, v105
	v_pk_add_f32 v[96:97], v[96:97], v[128:129]
	v_add_f32_e32 v108, 1.0, v108
	v_add_f32_e32 v109, 1.0, v109
	v_add_f32_e32 v110, 1.0, v110
	v_add_f32_e32 v111, 1.0, v111
	v_rcp_f32_e32 v113, v104
	v_add_f32_e32 v104, 1.0, v106
	v_mul_f32_e32 v96, 0xbfb8aa3b, v96
	v_rcp_f32_e32 v108, v108
	v_rcp_f32_e32 v109, v109
	v_rcp_f32_e32 v110, v110
	v_rcp_f32_e32 v111, v111
	v_rcp_f32_e32 v114, v104
	v_exp_f32_e32 v96, v96
	v_mul_f32_e32 v97, 0xbfb8aa3b, v97
	v_exp_f32_e32 v97, v97
	v_cvt_pk_bf16_f32 v104, v108, v109
	v_cvt_pk_bf16_f32 v105, v110, v111
	v_cvt_pk_bf16_f32 v106, v112, v107
	v_cvt_pk_bf16_f32 v107, v113, v114
	v_pk_add_f32 v[98:99], v[98:99], v[130:131]
	v_add_f32_e32 v96, 1.0, v96
	global_store_dwordx4 v[154:155], v[104:107], off offset:2048 sc1 nt
	v_pk_add_f32 v[102:103], v[102:103], v[134:135]
	v_pk_add_f32 v[100:101], v[100:101], v[132:133]
	v_rcp_f32_e32 v104, v96
	v_add_f32_e32 v96, 1.0, v97
	v_mul_f32_e32 v97, 0xbfb8aa3b, v98
	v_mul_f32_e32 v100, 0xbfb8aa3b, v100
	v_mul_f32_e32 v101, 0xbfb8aa3b, v101
	v_mul_f32_e32 v102, 0xbfb8aa3b, v102
	v_mul_f32_e32 v103, 0xbfb8aa3b, v103
	v_exp_f32_e32 v97, v97
	v_mul_f32_e32 v98, 0xbfb8aa3b, v99
	v_exp_f32_e32 v100, v100
; __device__ __forceinline__ unsigned cvt_pk_bf16(float lo, float hi) { f32x2_t v = {lo, hi}; bf16x2_t r = __builtin_convertvector(v, bf16x2_t); return __builtin_bit_cast(unsigned, r); }
; __device__ __forceinline__ float sigmoidf_(float v) { return __builtin_amdgcn_rcpf(1.0f + __builtin_amdgcn_exp2f(-1.4426950408889634f * v)); }
;     __device__ __forceinline__ void operator()(const f32x4 (&acc)[2][2][4][2], const Unit& u, int wr, int wc, int fr, int fq) const {
;     ...
;             for (int ai = 0; ai < 2; ++ai)
; #pragma unroll
;                 for (int m = 0; m < 4; ++m)
; #pragma unroll
;                     for (int bj = 0; bj < 2; ++bj) { const f32x4 v0 = acc[ai][bj][m][0] + bv[bj][0], v1 = acc[ai][bj][m][1] + bv[bj][1];
;                         u32x4 w; w.x = cvt_pk_bf16(sigmoidf_(v0[0]), sigmoidf_(v0[1])); w.y = cvt_pk_bf16(sigmoidf_(v0[2]), sigmoidf_(v0[3]));
;                         w.z = cvt_pk_bf16(sigmoidf_(v1[0]), sigmoidf_(v1[1])); w.w = cvt_pk_bf16(sigmoidf_(v1[2]), sigmoidf_(v1[3]));
;                         gf[((ai * 4 + m) * 2 + bj) * 64] = w; }
	v_exp_f32_e32 v101, v101
	v_exp_f32_e32 v102, v102
	v_exp_f32_e32 v103, v103
	v_exp_f32_e32 v98, v98
	v_pk_add_f32 v[94:95], v[94:95], v[142:143]
	v_rcp_f32_e32 v99, v96
	v_mul_f32_e32 v94, 0xbfb8aa3b, v94
	v_mul_f32_e32 v95, 0xbfb8aa3b, v95
	v_add_f32_e32 v96, 1.0, v97
	v_pk_add_f32 v[92:93], v[92:93], v[140:141]
	v_pk_add_f32 v[90:91], v[90:91], v[138:139]
	v_pk_add_f32 v[88:89], v[88:89], v[136:137]
	v_exp_f32_e32 v94, v94
	v_exp_f32_e32 v95, v95
	v_add_f32_e32 v100, 1.0, v100
	v_add_f32_e32 v101, 1.0, v101
	v_add_f32_e32 v102, 1.0, v102
	v_add_f32_e32 v103, 1.0, v103
	v_rcp_f32_e32 v105, v96
	v_add_f32_e32 v96, 1.0, v98
	v_mul_f32_e32 v92, 0xbfb8aa3b, v92
	v_mul_f32_e32 v93, 0xbfb8aa3b, v93
	v_mul_f32_e32 v88, 0xbfb8aa3b, v88
	v_mul_f32_e32 v89, 0xbfb8aa3b, v89
	v_mul_f32_e32 v90, 0xbfb8aa3b, v90
	v_rcp_f32_e32 v100, v100
	v_rcp_f32_e32 v101, v101
	v_rcp_f32_e32 v102, v102
	v_rcp_f32_e32 v103, v103
	v_rcp_f32_e32 v106, v96
	v_exp_f32_e32 v92, v92
	v_exp_f32_e32 v93, v93
	v_exp_f32_e32 v88, v88
	v_exp_f32_e32 v89, v89
	v_exp_f32_e32 v90, v90
	v_mul_f32_e32 v91, 0xbfb8aa3b, v91
	v_exp_f32_e32 v91, v91
	v_add_f32_e32 v94, 1.0, v94
	v_add_f32_e32 v95, 1.0, v95
	v_rcp_f32_e32 v94, v94
	v_rcp_f32_e32 v95, v95
	v_cvt_pk_bf16_f32 v96, v100, v101
	v_cvt_pk_bf16_f32 v97, v102, v103
	v_cvt_pk_bf16_f32 v98, v104, v99
	v_cvt_pk_bf16_f32 v99, v105, v106
	v_add_f32_e32 v92, 1.0, v92
	v_add_f32_e32 v93, 1.0, v93
	v_add_f32_e32 v88, 1.0, v88
	v_add_f32_e32 v89, 1.0, v89
	v_add_f32_e32 v90, 1.0, v90
	v_pk_add_f32 v[80:81], v[80:81], v[128:129]
	global_store_dwordx4 v[154:155], v[96:99], off offset:3072 sc1 nt
	v_rcp_f32_e32 v92, v92
	v_rcp_f32_e32 v93, v93
	v_rcp_f32_e32 v88, v88
	v_rcp_f32_e32 v89, v89
	v_rcp_f32_e32 v96, v90
	v_add_f32_e32 v90, 1.0, v91
	v_mul_f32_e32 v80, 0xbfb8aa3b, v80
	v_rcp_f32_e32 v97, v90
	v_exp_f32_e32 v80, v80
	v_mul_f32_e32 v81, 0xbfb8aa3b, v81
	v_cvt_pk_bf16_f32 v91, v94, v95
	v_add_co_u32_e32 v94, vcc, s33, v154
	v_exp_f32_e32 v81, v81
	s_nop 0
	v_addc_co_u32_e32 v95, vcc, 0, v155, vcc
	s_movk_i32 s2, 0x2000
	v_cvt_pk_bf16_f32 v90, v92, v93
	v_cvt_pk_bf16_f32 v92, v88, v89
	v_add_co_u32_e32 v88, vcc, s2, v154
	v_cvt_pk_bf16_f32 v93, v96, v97
	s_nop 0
	v_addc_co_u32_e32 v89, vcc, 0, v155, vcc
	v_pk_add_f32 v[82:83], v[82:83], v[130:131]
	v_add_f32_e32 v80, 1.0, v80
	global_store_dwordx4 v[88:89], v[90:93], off offset:-4096 sc1 nt
	v_pk_add_f32 v[86:87], v[86:87], v[134:135]
	v_pk_add_f32 v[84:85], v[84:85], v[132:133]
	v_rcp_f32_e32 v90, v80
	v_add_f32_e32 v80, 1.0, v81
	v_mul_f32_e32 v81, 0xbfb8aa3b, v82
	v_mul_f32_e32 v84, 0xbfb8aa3b, v84
	v_mul_f32_e32 v85, 0xbfb8aa3b, v85
	v_mul_f32_e32 v86, 0xbfb8aa3b, v86
	v_mul_f32_e32 v87, 0xbfb8aa3b, v87
	v_exp_f32_e32 v81, v81
	v_mul_f32_e32 v82, 0xbfb8aa3b, v83
	v_exp_f32_e32 v84, v84
	v_exp_f32_e32 v85, v85
	v_exp_f32_e32 v86, v86
	v_exp_f32_e32 v87, v87
	v_exp_f32_e32 v82, v82
	v_rcp_f32_e32 v83, v80
	v_add_f32_e32 v80, 1.0, v81
	v_pk_add_f32 v[72:73], v[72:73], v[136:137]
	v_add_f32_e32 v84, 1.0, v84
	v_add_f32_e32 v85, 1.0, v85
	v_add_f32_e32 v86, 1.0, v86
	v_add_f32_e32 v87, 1.0, v87
	v_rcp_f32_e32 v91, v80
	v_add_f32_e32 v80, 1.0, v82
	v_mul_f32_e32 v72, 0xbfb8aa3b, v72
	v_rcp_f32_e32 v84, v84
	v_rcp_f32_e32 v85, v85
	v_rcp_f32_e32 v86, v86
	v_rcp_f32_e32 v87, v87
	v_rcp_f32_e32 v92, v80
	v_exp_f32_e32 v72, v72
	v_mul_f32_e32 v73, 0xbfb8aa3b, v73
	v_exp_f32_e32 v73, v73
	v_cvt_pk_bf16_f32 v80, v84, v85
	v_cvt_pk_bf16_f32 v81, v86, v87
	v_cvt_pk_bf16_f32 v82, v90, v83
	v_cvt_pk_bf16_f32 v83, v91, v92
	v_pk_add_f32 v[74:75], v[74:75], v[138:139]
	v_add_f32_e32 v72, 1.0, v72
	global_store_dwordx4 v[94:95], v[80:83], off offset:1024 sc1 nt
	v_pk_add_f32 v[78:79], v[78:79], v[142:143]
	v_pk_add_f32 v[76:77], v[76:77], v[140:141]
	v_rcp_f32_e32 v80, v72
	v_add_f32_e32 v72, 1.0, v73
	v_mul_f32_e32 v73, 0xbfb8aa3b, v74
	v_mul_f32_e32 v76, 0xbfb8aa3b, v76
	v_mul_f32_e32 v77, 0xbfb8aa3b, v77
	v_mul_f32_e32 v78, 0xbfb8aa3b, v78
	v_mul_f32_e32 v79, 0xbfb8aa3b, v79
	v_exp_f32_e32 v73, v73
	v_mul_f32_e32 v74, 0xbfb8aa3b, v75
	v_exp_f32_e32 v76, v76
	v_exp_f32_e32 v77, v77
	v_exp_f32_e32 v78, v78
	v_exp_f32_e32 v79, v79
	v_exp_f32_e32 v74, v74
	v_rcp_f32_e32 v75, v72
	v_add_f32_e32 v72, 1.0, v73
	v_pk_add_f32 v[64:65], v[64:65], v[128:129]
	v_add_f32_e32 v76, 1.0, v76
	v_add_f32_e32 v77, 1.0, v77
	v_add_f32_e32 v78, 1.0, v78
	v_add_f32_e32 v79, 1.0, v79
	v_rcp_f32_e32 v81, v72
	v_add_f32_e32 v72, 1.0, v74
	v_mul_f32_e32 v64, 0xbfb8aa3b, v64
	v_rcp_f32_e32 v76, v76
	v_rcp_f32_e32 v77, v77
	v_rcp_f32_e32 v78, v78
	v_rcp_f32_e32 v79, v79
	v_rcp_f32_e32 v82, v72
	v_exp_f32_e32 v64, v64
	v_mul_f32_e32 v65, 0xbfb8aa3b, v65
	v_exp_f32_e32 v65, v65
	v_cvt_pk_bf16_f32 v72, v76, v77
	v_cvt_pk_bf16_f32 v73, v78, v79
	v_cvt_pk_bf16_f32 v74, v80, v75
	v_cvt_pk_bf16_f32 v75, v81, v82
	v_pk_add_f32 v[66:67], v[66:67], v[130:131]
	v_add_f32_e32 v64, 1.0, v64
	global_store_dwordx4 v[94:95], v[72:75], off offset:2048 sc1 nt
	v_pk_add_f32 v[70:71], v[70:71], v[134:135]
	v_pk_add_f32 v[68:69], v[68:69], v[132:133]
	v_rcp_f32_e32 v72, v64
	v_add_f32_e32 v64, 1.0, v65
	v_mul_f32_e32 v65, 0xbfb8aa3b, v66
	v_mul_f32_e32 v68, 0xbfb8aa3b, v68
	v_mul_f32_e32 v69, 0xbfb8aa3b, v69
	v_mul_f32_e32 v70, 0xbfb8aa3b, v70
	v_mul_f32_e32 v71, 0xbfb8aa3b, v71
	v_exp_f32_e32 v65, v65
	v_mul_f32_e32 v66, 0xbfb8aa3b, v67
	v_exp_f32_e32 v68, v68
	v_exp_f32_e32 v69, v69
	v_exp_f32_e32 v70, v70
	v_exp_f32_e32 v71, v71
	v_exp_f32_e32 v66, v66
	v_rcp_f32_e32 v67, v64
	v_add_f32_e32 v64, 1.0, v65
	v_pk_add_f32 v[56:57], v[56:57], v[136:137]
	v_add_f32_e32 v68, 1.0, v68
	v_add_f32_e32 v69, 1.0, v69
	v_add_f32_e32 v70, 1.0, v70
; __device__ __forceinline__ unsigned cvt_pk_bf16(float lo, float hi) { f32x2_t v = {lo, hi}; bf16x2_t r = __builtin_convertvector(v, bf16x2_t); return __builtin_bit_cast(unsigned, r); }
; __device__ __forceinline__ float sigmoidf_(float v) { return __builtin_amdgcn_rcpf(1.0f + __builtin_amdgcn_exp2f(-1.4426950408889634f * v)); }
;     __device__ __forceinline__ void operator()(const f32x4 (&acc)[2][2][4][2], const Unit& u, int wr, int wc, int fr, int fq) const {
;     ...
;             for (int ai = 0; ai < 2; ++ai)
; #pragma unroll
;                 for (int m = 0; m < 4; ++m)
; #pragma unroll
;                     for (int bj = 0; bj < 2; ++bj) { const f32x4 v0 = acc[ai][bj][m][0] + bv[bj][0], v1 = acc[ai][bj][m][1] + bv[bj][1];
;                         u32x4 w; w.x = cvt_pk_bf16(sigmoidf_(v0[0]), sigmoidf_(v0[1])); w.y = cvt_pk_bf16(sigmoidf_(v0[2]), sigmoidf_(v0[3]));
;                         w.z = cvt_pk_bf16(sigmoidf_(v1[0]), sigmoidf_(v1[1])); w.w = cvt_pk_bf16(sigmoidf_(v1[2]), sigmoidf_(v1[3]));
;                         gf[((ai * 4 + m) * 2 + bj) * 64] = w; }
	v_add_f32_e32 v71, 1.0, v71
	v_rcp_f32_e32 v73, v64
	v_add_f32_e32 v64, 1.0, v66
	v_mul_f32_e32 v56, 0xbfb8aa3b, v56
	v_rcp_f32_e32 v68, v68
	v_rcp_f32_e32 v69, v69
	v_rcp_f32_e32 v70, v70
	v_rcp_f32_e32 v71, v71
	v_rcp_f32_e32 v74, v64
	v_exp_f32_e32 v56, v56
	v_mul_f32_e32 v57, 0xbfb8aa3b, v57
	v_exp_f32_e32 v57, v57
	v_cvt_pk_bf16_f32 v64, v68, v69
	v_cvt_pk_bf16_f32 v65, v70, v71
	v_cvt_pk_bf16_f32 v66, v72, v67
	v_cvt_pk_bf16_f32 v67, v73, v74
	v_pk_add_f32 v[58:59], v[58:59], v[138:139]
	v_add_f32_e32 v56, 1.0, v56
	global_store_dwordx4 v[94:95], v[64:67], off offset:3072 sc1 nt
	v_pk_add_f32 v[62:63], v[62:63], v[142:143]
	v_pk_add_f32 v[60:61], v[60:61], v[140:141]
	v_rcp_f32_e32 v64, v56
	v_add_f32_e32 v56, 1.0, v57
	v_mul_f32_e32 v57, 0xbfb8aa3b, v58
	v_mul_f32_e32 v60, 0xbfb8aa3b, v60
	v_mul_f32_e32 v61, 0xbfb8aa3b, v61
	v_mul_f32_e32 v62, 0xbfb8aa3b, v62
	v_mul_f32_e32 v63, 0xbfb8aa3b, v63
	v_exp_f32_e32 v57, v57
	v_mul_f32_e32 v58, 0xbfb8aa3b, v59
	v_exp_f32_e32 v60, v60
	v_exp_f32_e32 v61, v61
	v_exp_f32_e32 v62, v62
	v_exp_f32_e32 v63, v63
	v_exp_f32_e32 v58, v58
	v_rcp_f32_e32 v59, v56
	v_add_f32_e32 v56, 1.0, v57
	v_pk_add_f32 v[48:49], v[48:49], v[128:129]
	v_add_f32_e32 v60, 1.0, v60
	v_add_f32_e32 v61, 1.0, v61
	v_add_f32_e32 v62, 1.0, v62
	v_add_f32_e32 v63, 1.0, v63
	v_rcp_f32_e32 v65, v56
	v_add_f32_e32 v56, 1.0, v58
	v_mul_f32_e32 v48, 0xbfb8aa3b, v48
	v_rcp_f32_e32 v60, v60
	v_rcp_f32_e32 v61, v61
	v_rcp_f32_e32 v62, v62
	v_rcp_f32_e32 v63, v63
	v_rcp_f32_e32 v66, v56
	v_exp_f32_e32 v48, v48
	v_mul_f32_e32 v49, 0xbfb8aa3b, v49
	v_exp_f32_e32 v49, v49
	v_cvt_pk_bf16_f32 v56, v60, v61
	v_cvt_pk_bf16_f32 v57, v62, v63
	v_cvt_pk_bf16_f32 v58, v64, v59
	v_cvt_pk_bf16_f32 v59, v65, v66
	v_pk_add_f32 v[50:51], v[50:51], v[130:131]
	v_add_f32_e32 v48, 1.0, v48
	global_store_dwordx4 v[88:89], v[56:59], off sc1 nt
	v_pk_add_f32 v[54:55], v[54:55], v[134:135]
	v_pk_add_f32 v[52:53], v[52:53], v[132:133]
	v_rcp_f32_e32 v56, v48
	v_add_f32_e32 v48, 1.0, v49
	v_mul_f32_e32 v49, 0xbfb8aa3b, v50
	v_mul_f32_e32 v52, 0xbfb8aa3b, v52
	v_mul_f32_e32 v53, 0xbfb8aa3b, v53
	v_mul_f32_e32 v54, 0xbfb8aa3b, v54
	v_mul_f32_e32 v55, 0xbfb8aa3b, v55
	v_exp_f32_e32 v49, v49
	v_mul_f32_e32 v50, 0xbfb8aa3b, v51
	v_exp_f32_e32 v52, v52
	v_exp_f32_e32 v53, v53
	v_exp_f32_e32 v54, v54
	v_exp_f32_e32 v55, v55
	v_exp_f32_e32 v50, v50
	v_rcp_f32_e32 v51, v48
	v_add_f32_e32 v48, 1.0, v49
	v_pk_add_f32 v[40:41], v[40:41], v[136:137]
	v_add_f32_e32 v52, 1.0, v52
	v_add_f32_e32 v53, 1.0, v53
	v_add_f32_e32 v54, 1.0, v54
	v_add_f32_e32 v55, 1.0, v55
	v_rcp_f32_e32 v57, v48
	v_add_f32_e32 v48, 1.0, v50
	v_mul_f32_e32 v40, 0xbfb8aa3b, v40
	v_rcp_f32_e32 v52, v52
	v_rcp_f32_e32 v53, v53
	v_rcp_f32_e32 v54, v54
	v_rcp_f32_e32 v55, v55
	v_rcp_f32_e32 v58, v48
	v_exp_f32_e32 v40, v40
	v_mul_f32_e32 v41, 0xbfb8aa3b, v41
	v_exp_f32_e32 v41, v41
	v_cvt_pk_bf16_f32 v48, v52, v53
	v_cvt_pk_bf16_f32 v49, v54, v55
	v_cvt_pk_bf16_f32 v50, v56, v51
	v_cvt_pk_bf16_f32 v51, v57, v58
	v_pk_add_f32 v[42:43], v[42:43], v[138:139]
	v_add_f32_e32 v40, 1.0, v40
	global_store_dwordx4 v[88:89], v[48:51], off offset:1024 sc1 nt
	v_pk_add_f32 v[46:47], v[46:47], v[142:143]
	v_pk_add_f32 v[44:45], v[44:45], v[140:141]
	v_rcp_f32_e32 v48, v40
	v_add_f32_e32 v40, 1.0, v41
	v_mul_f32_e32 v41, 0xbfb8aa3b, v42
	v_mul_f32_e32 v44, 0xbfb8aa3b, v44
	v_mul_f32_e32 v45, 0xbfb8aa3b, v45
	v_mul_f32_e32 v46, 0xbfb8aa3b, v46
	v_mul_f32_e32 v47, 0xbfb8aa3b, v47
	v_exp_f32_e32 v41, v41
	v_mul_f32_e32 v42, 0xbfb8aa3b, v43
	v_exp_f32_e32 v44, v44
	v_exp_f32_e32 v45, v45
	v_exp_f32_e32 v46, v46
	v_exp_f32_e32 v47, v47
	v_exp_f32_e32 v42, v42
	v_rcp_f32_e32 v43, v40
	v_add_f32_e32 v40, 1.0, v41
	v_pk_add_f32 v[32:33], v[32:33], v[128:129]
	v_add_f32_e32 v44, 1.0, v44
	v_add_f32_e32 v45, 1.0, v45
	v_add_f32_e32 v46, 1.0, v46
	v_add_f32_e32 v47, 1.0, v47
	v_rcp_f32_e32 v49, v40
	v_add_f32_e32 v40, 1.0, v42
	v_mul_f32_e32 v32, 0xbfb8aa3b, v32
	v_rcp_f32_e32 v44, v44
	v_rcp_f32_e32 v45, v45
	v_rcp_f32_e32 v46, v46
	v_rcp_f32_e32 v47, v47
	v_rcp_f32_e32 v50, v40
	v_exp_f32_e32 v32, v32
	v_mul_f32_e32 v33, 0xbfb8aa3b, v33
	v_exp_f32_e32 v33, v33
	v_cvt_pk_bf16_f32 v40, v44, v45
	v_cvt_pk_bf16_f32 v41, v46, v47
	v_cvt_pk_bf16_f32 v42, v48, v43
	v_cvt_pk_bf16_f32 v43, v49, v50
	v_pk_add_f32 v[34:35], v[34:35], v[130:131]
	v_add_f32_e32 v32, 1.0, v32
	global_store_dwordx4 v[88:89], v[40:43], off offset:2048 sc1 nt
	v_pk_add_f32 v[38:39], v[38:39], v[134:135]
	v_pk_add_f32 v[36:37], v[36:37], v[132:133]
	v_rcp_f32_e32 v40, v32
	v_add_f32_e32 v32, 1.0, v33
	v_mul_f32_e32 v33, 0xbfb8aa3b, v34
	v_mul_f32_e32 v36, 0xbfb8aa3b, v36
	v_mul_f32_e32 v37, 0xbfb8aa3b, v37
	v_mul_f32_e32 v38, 0xbfb8aa3b, v38
	v_mul_f32_e32 v39, 0xbfb8aa3b, v39
	v_exp_f32_e32 v33, v33
	v_mul_f32_e32 v34, 0xbfb8aa3b, v35
	v_exp_f32_e32 v36, v36
	v_exp_f32_e32 v37, v37
	v_exp_f32_e32 v38, v38
	v_exp_f32_e32 v39, v39
	v_exp_f32_e32 v34, v34
	v_rcp_f32_e32 v35, v32
	v_add_f32_e32 v32, 1.0, v33
	v_pk_add_f32 v[24:25], v[24:25], v[136:137]
	v_add_f32_e32 v36, 1.0, v36
	v_add_f32_e32 v37, 1.0, v37
	v_add_f32_e32 v38, 1.0, v38
	v_add_f32_e32 v39, 1.0, v39
	v_rcp_f32_e32 v41, v32
	v_add_f32_e32 v32, 1.0, v34
	v_mul_f32_e32 v24, 0xbfb8aa3b, v24
	v_rcp_f32_e32 v36, v36
	v_rcp_f32_e32 v37, v37
	v_rcp_f32_e32 v38, v38
	v_rcp_f32_e32 v39, v39
; __device__ __forceinline__ unsigned cvt_pk_bf16(float lo, float hi) { f32x2_t v = {lo, hi}; bf16x2_t r = __builtin_convertvector(v, bf16x2_t); return __builtin_bit_cast(unsigned, r); }
; __device__ __forceinline__ float sigmoidf_(float v) { return __builtin_amdgcn_rcpf(1.0f + __builtin_amdgcn_exp2f(-1.4426950408889634f * v)); }
;     __device__ __forceinline__ void operator()(const f32x4 (&acc)[2][2][4][2], const Unit& u, int wr, int wc, int fr, int fq) const {
;     ...
;             for (int ai = 0; ai < 2; ++ai)
; #pragma unroll
;                 for (int m = 0; m < 4; ++m)
; #pragma unroll
;                     for (int bj = 0; bj < 2; ++bj) { const f32x4 v0 = acc[ai][bj][m][0] + bv[bj][0], v1 = acc[ai][bj][m][1] + bv[bj][1];
;                         u32x4 w; w.x = cvt_pk_bf16(sigmoidf_(v0[0]), sigmoidf_(v0[1])); w.y = cvt_pk_bf16(sigmoidf_(v0[2]), sigmoidf_(v0[3]));
;                         w.z = cvt_pk_bf16(sigmoidf_(v1[0]), sigmoidf_(v1[1])); w.w = cvt_pk_bf16(sigmoidf_(v1[2]), sigmoidf_(v1[3]));
;                         gf[((ai * 4 + m) * 2 + bj) * 64] = w; }
;             return;
	v_rcp_f32_e32 v42, v32
	v_exp_f32_e32 v24, v24
	v_mul_f32_e32 v25, 0xbfb8aa3b, v25
	v_exp_f32_e32 v25, v25
	v_cvt_pk_bf16_f32 v32, v36, v37
	v_cvt_pk_bf16_f32 v33, v38, v39
	v_cvt_pk_bf16_f32 v34, v40, v35
	v_cvt_pk_bf16_f32 v35, v41, v42
	v_pk_add_f32 v[28:29], v[28:29], v[140:141]
	v_pk_add_f32 v[26:27], v[26:27], v[138:139]
	v_add_f32_e32 v24, 1.0, v24
	global_store_dwordx4 v[88:89], v[32:35], off offset:3072 sc1 nt
	v_pk_add_f32 v[30:31], v[30:31], v[142:143]
	v_mul_f32_e32 v28, 0xbfb8aa3b, v28
	v_mul_f32_e32 v29, 0xbfb8aa3b, v29
	v_rcp_f32_e32 v32, v24
	v_add_f32_e32 v24, 1.0, v25
	v_mul_f32_e32 v25, 0xbfb8aa3b, v26
	v_exp_f32_e32 v28, v28
	v_exp_f32_e32 v29, v29
	v_mul_f32_e32 v30, 0xbfb8aa3b, v30
	v_mul_f32_e32 v31, 0xbfb8aa3b, v31
	v_exp_f32_e32 v25, v25
	v_mul_f32_e32 v26, 0xbfb8aa3b, v27
	v_exp_f32_e32 v30, v30
	v_exp_f32_e32 v31, v31
	v_exp_f32_e32 v26, v26
	v_add_f32_e32 v28, 1.0, v28
	v_add_f32_e32 v29, 1.0, v29
	v_rcp_f32_e32 v27, v24
	v_add_f32_e32 v24, 1.0, v25
	v_pk_add_f32 v[16:17], v[16:17], v[128:129]
	v_rcp_f32_e32 v28, v28
	v_rcp_f32_e32 v29, v29
	v_add_f32_e32 v30, 1.0, v30
	v_add_f32_e32 v31, 1.0, v31
	v_rcp_f32_e32 v33, v24
	v_add_f32_e32 v24, 1.0, v26
	v_mul_f32_e32 v16, 0xbfb8aa3b, v16
	v_rcp_f32_e32 v30, v30
	v_rcp_f32_e32 v31, v31
	v_rcp_f32_e32 v34, v24
	v_exp_f32_e32 v16, v16
	v_mul_f32_e32 v17, 0xbfb8aa3b, v17
	v_exp_f32_e32 v17, v17
	s_movk_i32 s2, 0x3000
	v_cvt_pk_bf16_f32 v24, v28, v29
	v_add_co_u32_e32 v28, vcc, s2, v154
	v_cvt_pk_bf16_f32 v25, v30, v31
	v_cvt_pk_bf16_f32 v26, v32, v27
	v_cvt_pk_bf16_f32 v27, v33, v34
	v_addc_co_u32_e32 v29, vcc, 0, v155, vcc
	v_pk_add_f32 v[18:19], v[18:19], v[130:131]
	v_add_f32_e32 v16, 1.0, v16
	global_store_dwordx4 v[28:29], v[24:27], off sc1 nt
	v_pk_add_f32 v[22:23], v[22:23], v[134:135]
	v_pk_add_f32 v[20:21], v[20:21], v[132:133]
	v_rcp_f32_e32 v24, v16
	v_add_f32_e32 v16, 1.0, v17
	v_mul_f32_e32 v17, 0xbfb8aa3b, v18
	v_mul_f32_e32 v20, 0xbfb8aa3b, v20
	v_mul_f32_e32 v21, 0xbfb8aa3b, v21
	v_mul_f32_e32 v22, 0xbfb8aa3b, v22
	v_mul_f32_e32 v23, 0xbfb8aa3b, v23
	v_exp_f32_e32 v17, v17
	v_mul_f32_e32 v18, 0xbfb8aa3b, v19
	v_exp_f32_e32 v20, v20
	v_exp_f32_e32 v21, v21
	v_exp_f32_e32 v22, v22
	v_exp_f32_e32 v23, v23
	v_exp_f32_e32 v18, v18
	v_rcp_f32_e32 v19, v16
	v_add_f32_e32 v16, 1.0, v17
	v_pk_add_f32 v[8:9], v[8:9], v[136:137]
	v_add_f32_e32 v20, 1.0, v20
	v_add_f32_e32 v21, 1.0, v21
	v_add_f32_e32 v22, 1.0, v22
	v_add_f32_e32 v23, 1.0, v23
	v_rcp_f32_e32 v25, v16
	v_add_f32_e32 v16, 1.0, v18
	v_mul_f32_e32 v8, 0xbfb8aa3b, v8
	v_rcp_f32_e32 v20, v20
	v_rcp_f32_e32 v21, v21
	v_rcp_f32_e32 v22, v22
	v_rcp_f32_e32 v23, v23
	v_rcp_f32_e32 v26, v16
	v_exp_f32_e32 v8, v8
	v_mul_f32_e32 v9, 0xbfb8aa3b, v9
	v_exp_f32_e32 v9, v9
	v_cvt_pk_bf16_f32 v16, v20, v21
	v_cvt_pk_bf16_f32 v17, v22, v23
	v_cvt_pk_bf16_f32 v18, v24, v19
	v_cvt_pk_bf16_f32 v19, v25, v26
	v_pk_add_f32 v[10:11], v[10:11], v[138:139]
	v_add_f32_e32 v8, 1.0, v8
	global_store_dwordx4 v[28:29], v[16:19], off offset:1024 sc1 nt
	v_pk_add_f32 v[14:15], v[14:15], v[142:143]
	v_pk_add_f32 v[12:13], v[12:13], v[140:141]
	v_rcp_f32_e32 v16, v8
	v_add_f32_e32 v8, 1.0, v9
	v_mul_f32_e32 v9, 0xbfb8aa3b, v10
	v_mul_f32_e32 v12, 0xbfb8aa3b, v12
	v_mul_f32_e32 v13, 0xbfb8aa3b, v13
	v_mul_f32_e32 v14, 0xbfb8aa3b, v14
	v_mul_f32_e32 v15, 0xbfb8aa3b, v15
	v_exp_f32_e32 v9, v9
	v_mul_f32_e32 v10, 0xbfb8aa3b, v11
	v_exp_f32_e32 v12, v12
	v_exp_f32_e32 v13, v13
	v_exp_f32_e32 v14, v14
	v_exp_f32_e32 v15, v15
	v_exp_f32_e32 v10, v10
	v_rcp_f32_e32 v11, v8
	v_add_f32_e32 v8, 1.0, v9
	v_pk_add_f32 v[0:1], v[0:1], v[128:129]
	v_add_f32_e32 v12, 1.0, v12
	v_add_f32_e32 v13, 1.0, v13
	v_add_f32_e32 v14, 1.0, v14
	v_add_f32_e32 v15, 1.0, v15
	v_rcp_f32_e32 v17, v8
	v_add_f32_e32 v8, 1.0, v10
	v_mul_f32_e32 v0, 0xbfb8aa3b, v0
	v_rcp_f32_e32 v12, v12
	v_rcp_f32_e32 v13, v13
	v_rcp_f32_e32 v14, v14
	v_rcp_f32_e32 v15, v15
	v_rcp_f32_e32 v18, v8
	v_exp_f32_e32 v0, v0
	v_mul_f32_e32 v1, 0xbfb8aa3b, v1
	v_exp_f32_e32 v1, v1
	v_cvt_pk_bf16_f32 v8, v12, v13
	v_cvt_pk_bf16_f32 v9, v14, v15
	v_cvt_pk_bf16_f32 v10, v16, v11
	v_cvt_pk_bf16_f32 v11, v17, v18
	v_pk_add_f32 v[2:3], v[2:3], v[130:131]
	v_add_f32_e32 v0, 1.0, v0
	global_store_dwordx4 v[28:29], v[8:11], off offset:2048 sc1 nt
	v_pk_add_f32 v[6:7], v[6:7], v[134:135]
	v_pk_add_f32 v[4:5], v[4:5], v[132:133]
	v_rcp_f32_e32 v8, v0
	v_add_f32_e32 v0, 1.0, v1
	v_mul_f32_e32 v1, 0xbfb8aa3b, v2
	v_mul_f32_e32 v4, 0xbfb8aa3b, v4
	v_mul_f32_e32 v5, 0xbfb8aa3b, v5
	v_mul_f32_e32 v6, 0xbfb8aa3b, v6
	v_mul_f32_e32 v7, 0xbfb8aa3b, v7
	v_exp_f32_e32 v1, v1
	v_mul_f32_e32 v2, 0xbfb8aa3b, v3
	v_exp_f32_e32 v4, v4
	v_exp_f32_e32 v5, v5
	v_exp_f32_e32 v6, v6
	v_exp_f32_e32 v7, v7
	v_exp_f32_e32 v2, v2
	v_rcp_f32_e32 v3, v0
	v_add_f32_e32 v0, 1.0, v1
	v_add_f32_e32 v4, 1.0, v4
	v_add_f32_e32 v5, 1.0, v5
	v_add_f32_e32 v6, 1.0, v6
	v_add_f32_e32 v7, 1.0, v7
	v_rcp_f32_e32 v9, v0
	v_add_f32_e32 v0, 1.0, v2
	v_rcp_f32_e32 v4, v4
	v_rcp_f32_e32 v5, v5
	v_rcp_f32_e32 v6, v6
	v_rcp_f32_e32 v7, v7
	v_rcp_f32_e32 v10, v0
	v_cvt_pk_bf16_f32 v0, v4, v5
	v_cvt_pk_bf16_f32 v2, v8, v3
	v_cvt_pk_bf16_f32 v1, v6, v7
	v_cvt_pk_bf16_f32 v3, v9, v10
	global_store_dwordx4 v[28:29], v[0:3], off offset:3072 sc1 nt
	s_andn2_b64 vcc, exec, s[36:37]
	s_mov_b64 s[2:3], -1
	s_cbranch_vccnz .LBB0_343
